# phase 0 gate-matrix transpose job (64 blocks): 32 strided loads per thread issued together via immediate offsets, counted waits
# speedup vs baseline: 1.0077x; 1.0014x over previous
.LBB0_38:
	v_and_b32_e32 v4, 0x7f, v0
	v_lshlrev_b32_e32 v4, 7, v4
	v_lshrrev_b32_e32 v5, 7, v0
	v_add_lshl_u32 v4, v4, v5, 2
	s_mov_b64 s[6:7], 0x400
	global_load_dword v64, v4, s[2:3]
	global_load_dword v65, v4, s[2:3] offset:16
	global_load_dword v66, v4, s[2:3] offset:32
	global_load_dword v67, v4, s[2:3] offset:48
	global_load_dword v68, v4, s[2:3] offset:64
	global_load_dword v69, v4, s[2:3] offset:80
	global_load_dword v70, v4, s[2:3] offset:96
	global_load_dword v71, v4, s[2:3] offset:112
	global_load_dword v72, v4, s[2:3] offset:128
	global_load_dword v73, v4, s[2:3] offset:144
	global_load_dword v74, v4, s[2:3] offset:160
	global_load_dword v75, v4, s[2:3] offset:176
	global_load_dword v76, v4, s[2:3] offset:192
	global_load_dword v77, v4, s[2:3] offset:208
	global_load_dword v78, v4, s[2:3] offset:224
	global_load_dword v79, v4, s[2:3] offset:240
	global_load_dword v80, v4, s[2:3] offset:256
	global_load_dword v81, v4, s[2:3] offset:272
	global_load_dword v82, v4, s[2:3] offset:288
	global_load_dword v83, v4, s[2:3] offset:304
	global_load_dword v84, v4, s[2:3] offset:320
	global_load_dword v85, v4, s[2:3] offset:336
	global_load_dword v86, v4, s[2:3] offset:352
	global_load_dword v87, v4, s[2:3] offset:368
	global_load_dword v88, v4, s[2:3] offset:384
	global_load_dword v89, v4, s[2:3] offset:400
	global_load_dword v90, v4, s[2:3] offset:416
	global_load_dword v91, v4, s[2:3] offset:432
	global_load_dword v92, v4, s[2:3] offset:448
	global_load_dword v93, v4, s[2:3] offset:464
	global_load_dword v94, v4, s[2:3] offset:480
	global_load_dword v96, v4, s[2:3] offset:496
	s_waitcnt vmcnt(31)
	v_cvt_pk_bf16_f32 v64, v64, v13
	global_store_short v[2:3], v64, off
	v_lshl_add_u64 v[2:3], v[2:3], 0, s[6:7]
	s_waitcnt vmcnt(31)
	v_cvt_pk_bf16_f32 v65, v65, v13
	global_store_short v[2:3], v65, off
	v_lshl_add_u64 v[2:3], v[2:3], 0, s[6:7]
	s_waitcnt vmcnt(31)
	v_cvt_pk_bf16_f32 v66, v66, v13
	global_store_short v[2:3], v66, off
	v_lshl_add_u64 v[2:3], v[2:3], 0, s[6:7]
	s_waitcnt vmcnt(31)
	v_cvt_pk_bf16_f32 v67, v67, v13
	global_store_short v[2:3], v67, off
	v_lshl_add_u64 v[2:3], v[2:3], 0, s[6:7]
	s_waitcnt vmcnt(31)
	v_cvt_pk_bf16_f32 v68, v68, v13
	global_store_short v[2:3], v68, off
	v_lshl_add_u64 v[2:3], v[2:3], 0, s[6:7]
	s_waitcnt vmcnt(31)
	v_cvt_pk_bf16_f32 v69, v69, v13
	global_store_short v[2:3], v69, off
	v_lshl_add_u64 v[2:3], v[2:3], 0, s[6:7]
	s_waitcnt vmcnt(31)
	v_cvt_pk_bf16_f32 v70, v70, v13
	global_store_short v[2:3], v70, off
	v_lshl_add_u64 v[2:3], v[2:3], 0, s[6:7]
	s_waitcnt vmcnt(31)
	v_cvt_pk_bf16_f32 v71, v71, v13
	global_store_short v[2:3], v71, off
	v_lshl_add_u64 v[2:3], v[2:3], 0, s[6:7]
	s_waitcnt vmcnt(31)
	v_cvt_pk_bf16_f32 v72, v72, v13
	global_store_short v[2:3], v72, off
	v_lshl_add_u64 v[2:3], v[2:3], 0, s[6:7]
	s_waitcnt vmcnt(31)
	v_cvt_pk_bf16_f32 v73, v73, v13
	global_store_short v[2:3], v73, off
	v_lshl_add_u64 v[2:3], v[2:3], 0, s[6:7]
	s_waitcnt vmcnt(31)
	v_cvt_pk_bf16_f32 v74, v74, v13
	global_store_short v[2:3], v74, off
	v_lshl_add_u64 v[2:3], v[2:3], 0, s[6:7]
	s_waitcnt vmcnt(31)
	v_cvt_pk_bf16_f32 v75, v75, v13
	global_store_short v[2:3], v75, off
	v_lshl_add_u64 v[2:3], v[2:3], 0, s[6:7]
	s_waitcnt vmcnt(31)
	v_cvt_pk_bf16_f32 v76, v76, v13
	global_store_short v[2:3], v76, off
	v_lshl_add_u64 v[2:3], v[2:3], 0, s[6:7]
	s_waitcnt vmcnt(31)
	v_cvt_pk_bf16_f32 v77, v77, v13
	global_store_short v[2:3], v77, off
	v_lshl_add_u64 v[2:3], v[2:3], 0, s[6:7]
	s_waitcnt vmcnt(31)
	v_cvt_pk_bf16_f32 v78, v78, v13
	global_store_short v[2:3], v78, off
	v_lshl_add_u64 v[2:3], v[2:3], 0, s[6:7]
	s_waitcnt vmcnt(31)
	v_cvt_pk_bf16_f32 v79, v79, v13
	global_store_short v[2:3], v79, off
	v_lshl_add_u64 v[2:3], v[2:3], 0, s[6:7]
	s_waitcnt vmcnt(31)
	v_cvt_pk_bf16_f32 v80, v80, v13
	global_store_short v[2:3], v80, off
	v_lshl_add_u64 v[2:3], v[2:3], 0, s[6:7]
	s_waitcnt vmcnt(31)
	v_cvt_pk_bf16_f32 v81, v81, v13
	global_store_short v[2:3], v81, off
	v_lshl_add_u64 v[2:3], v[2:3], 0, s[6:7]
	s_waitcnt vmcnt(31)
	v_cvt_pk_bf16_f32 v82, v82, v13
	global_store_short v[2:3], v82, off
	v_lshl_add_u64 v[2:3], v[2:3], 0, s[6:7]
	s_waitcnt vmcnt(31)
	v_cvt_pk_bf16_f32 v83, v83, v13
	global_store_short v[2:3], v83, off
	v_lshl_add_u64 v[2:3], v[2:3], 0, s[6:7]
	s_waitcnt vmcnt(31)
	v_cvt_pk_bf16_f32 v84, v84, v13
	global_store_short v[2:3], v84, off
	v_lshl_add_u64 v[2:3], v[2:3], 0, s[6:7]
	s_waitcnt vmcnt(31)
	v_cvt_pk_bf16_f32 v85, v85, v13
	global_store_short v[2:3], v85, off
	v_lshl_add_u64 v[2:3], v[2:3], 0, s[6:7]
	s_waitcnt vmcnt(31)
	v_cvt_pk_bf16_f32 v86, v86, v13
	global_store_short v[2:3], v86, off
	v_lshl_add_u64 v[2:3], v[2:3], 0, s[6:7]
	s_waitcnt vmcnt(31)
	v_cvt_pk_bf16_f32 v87, v87, v13
	global_store_short v[2:3], v87, off
	v_lshl_add_u64 v[2:3], v[2:3], 0, s[6:7]
	s_waitcnt vmcnt(31)
	v_cvt_pk_bf16_f32 v88, v88, v13
	global_store_short v[2:3], v88, off
	v_lshl_add_u64 v[2:3], v[2:3], 0, s[6:7]
	s_waitcnt vmcnt(31)
	v_cvt_pk_bf16_f32 v89, v89, v13
	global_store_short v[2:3], v89, off
	v_lshl_add_u64 v[2:3], v[2:3], 0, s[6:7]
	s_waitcnt vmcnt(31)
	v_cvt_pk_bf16_f32 v90, v90, v13
	global_store_short v[2:3], v90, off
	v_lshl_add_u64 v[2:3], v[2:3], 0, s[6:7]
	s_waitcnt vmcnt(31)
	v_cvt_pk_bf16_f32 v91, v91, v13
	global_store_short v[2:3], v91, off
	v_lshl_add_u64 v[2:3], v[2:3], 0, s[6:7]
	s_waitcnt vmcnt(31)
	v_cvt_pk_bf16_f32 v92, v92, v13
	global_store_short v[2:3], v92, off
	v_lshl_add_u64 v[2:3], v[2:3], 0, s[6:7]
	s_waitcnt vmcnt(31)
	v_cvt_pk_bf16_f32 v93, v93, v13
	global_store_short v[2:3], v93, off
	v_lshl_add_u64 v[2:3], v[2:3], 0, s[6:7]
	s_waitcnt vmcnt(31)
	v_cvt_pk_bf16_f32 v94, v94, v13
	global_store_short v[2:3], v94, off
	v_lshl_add_u64 v[2:3], v[2:3], 0, s[6:7]
	s_waitcnt vmcnt(31)
	v_cvt_pk_bf16_f32 v96, v96, v13
	global_store_short v[2:3], v96, off
	v_lshl_add_u64 v[2:3], v[2:3], 0, s[6:7]
